# P4 prologue/epilogue de-serialisation: gm = n2g*(mod+1) computed in the GEMM prologue and kept in VGPRs free across the K-loop; epilogue head issues the 4 gate loads and 16 residual loads back to back
# baseline (speedup 1.0000x reference)
; #define PG8_STAGE(bufoff, gbase, voff) do { _Pragma("unroll") for (int _i = 0; _i < 2; ++_i) \
;         __builtin_amdgcn_global_load_lds((const unsigned*)((const char*)(gbase) + (voff)[_i]), (PG8_LAS unsigned*)(lds + (bufoff) + ldsw + _i * 8192), 16, 0, 0); } while (0)
; #define PG8_WAIT_V(n) asm volatile("s_waitcnt vmcnt(" #n ")" ::: "memory")
; #define PG8_BAR __builtin_amdgcn_s_barrier()
; template <class Epi, class Sched, bool ALIGN_EPI = false, bool SP2 = false>
; __device__ __forceinline__ void gemm_phase(PG8_LAS unsigned char* lds, const Gemm g, const Sched& S, const Epi& E) {
;     ...
;         PG8_STAGE(PG8_SB(0, 0), cB, voffB); PG8_STAGE(PG8_SB(0, 1), cB + hstep, voffB); PG8_STAGE(PG8_SA(0, 0), cA, voffA); PG8_STAGE(PG8_SA(0, 1), cA + hstep, voffA);
;         if (wr == 1) PG8_BAR;
;         PG8_WAIT_V(2); PG8_BAR;
;         PG8_STAGE(PG8_SB(1, 0), cB + kstep, voffB); PG8_STAGE(PG8_SA(1, 0), cA + kstep, voffA); PG8_STAGE(PG8_SB(1, 1), cB + hstep + kstep, voffB);
;         PG8_WAIT_V(6); PG8_BAR;
;     } else {
;         PG8_STAGE(PG8_SB(0, 0), cB, voffB); PG8_STAGE(PG8_SA(0, 0), cA, voffA); PG8_STAGE(PG8_SB(0, 1), cB + hstep, voffB); PG8_STAGE(PG8_SA(0, 1), cA + hstep, voffA);
;         if (wr == 1) PG8_BAR;
;         PG8_WAIT_V(4); PG8_BAR;
;         PG8_STAGE(PG8_SB(1, 0), cB + kstep, voffB); PG8_STAGE(PG8_SA(1, 0), cA + kstep, voffA); PG8_STAGE(PG8_SB(1, 1), cB + hstep + kstep, voffB);
;         PG8_WAIT_V(6); PG8_BAR;
;     }
;     __device__ __forceinline__ void operator()(const f32x4 (&acc)[2][2][4][2], const pg8::Unit& u, int wr, int wc, int fr, int fq) const {
;     ...
;         f32x4 g1v[2][2], gm[2][2];
; #pragma unroll
;         for (int bj = 0; bj < 2; ++bj)
; #pragma unroll
;             for (int n = 0; n < 2; ++n) { const int col = colb + 128 * bj + 4 * n; g1v[bj][n] = *(const f32x4*)(mb + 2048 + col);
;                 gm[bj][n] = *(const f32x4*)(n2g + col) * (*(const f32x4*)(mb + 4096 + col) + 1.f); }
.LBB0_448:
	s_add_u32 s12, s36, 0x4000000
	s_addc_u32 s0, s37, 0
	s_add_u32 s16, s36, 0x2000000
	s_addc_u32 s1, s37, 0
	s_add_u32 s40, s36, 0x1f00000
	s_addc_u32 s41, s37, 0
	s_add_u32 s20, s36, 0x1e80000
	s_mov_b64 s[42:43], 0x80
	s_addc_u32 s11, s37, 0
	s_and_b32 s63, s8, 3
	s_add_i32 m0, s28, 0x18000
	v_lshl_add_u64 v[6:7], v[6:7], 0, s[42:43]
	s_lshl_b32 s64, s9, 6
	s_lshl_b32 s13, s9, 13
	s_lshl_b32 s15, s63, 12
	v_bfe_u32 v16, v9, 4, 2
	v_lshlrev_b32_e32 v16, 3, v16
	v_lshl_or_b32 v16, s63, 5, v16
	v_lshl_or_b32 v16, s14, 8, v16
	v_lshlrev_b32_e32 v17, 2, v16
	s_lshr_b32 s84, s22, 3
	s_mul_i32 s84, s84, 0x6000
	s_add_u32 s84, s36, s84
	s_addc_u32 s85, s37, 0
	s_add_u32 s84, s84, 0x4000
	s_addc_u32 s85, s85, 0
	global_load_dwordx4 v[20:23], v17, s[34:35]
	global_load_dwordx4 v[24:27], v17, s[34:35] offset:16
	global_load_dwordx4 v[28:31], v17, s[34:35] offset:512
	global_load_dwordx4 v[32:35], v17, s[34:35] offset:528
	global_load_dwordx4 v[36:39], v17, s[84:85]
	global_load_dwordx4 v[40:43], v17, s[84:85] offset:16
	global_load_dwordx4 v[44:47], v17, s[84:85] offset:512
	global_load_dwordx4 v[48:51], v17, s[84:85] offset:528
	s_waitcnt vmcnt(10)
	s_barrier
	global_load_lds_dwordx4 v[6:7], off
	v_lshl_add_u64 v[4:5], v[4:5], 0, s[42:43]
	s_add_i32 m0, s28, 0x1a000
	s_add_i32 s65, s28, 0x8000
	s_add_i32 s66, s28, 0xa000
	global_load_lds_dwordx4 v[4:5], off
	v_lshl_add_u64 v[0:1], v[0:1], 0, s[42:43]
	s_mov_b32 m0, s65
	s_add_u32 s8, s56, 0x40080
	global_load_lds_dwordx4 v[0:1], off
	v_lshl_add_u64 v[0:1], v[2:3], 0, s[42:43]
	s_mov_b32 m0, s66
	s_addc_u32 s9, s57, 0
	global_load_lds_dwordx4 v[0:1], off
	s_add_i32 m0, s28, 0x1c000
	v_lshl_add_u64 v[0:1], s[8:9], 0, v[212:213]
	global_load_lds_dwordx4 v[0:1], off
	v_lshl_add_u64 v[0:1], s[8:9], 0, v[216:217]
	s_add_i32 m0, s28, 0x1e000
	v_and_b32_e32 v246, 15, v9
	global_load_lds_dwordx4 v[0:1], off
	v_bfe_u32 v0, v9, 4, 2
	v_lshlrev_b32_e32 v1, 3, v0
	v_lshlrev_b32_e32 v2, 4, v0
	v_cmp_eq_u32_e64 s[8:9], 0, v0
	v_lshlrev_b32_e32 v0, 8, v8
	v_lshlrev_b32_e32 v3, 2, v9
	v_lshl_or_b32 v248, s63, 5, v1
	v_and_b32_e32 v0, 0x18000, v0
	v_lshlrev_b32_e32 v1, 11, v12
	v_lshl_or_b32 v2, v246, 6, v2
	v_and_b32_e32 v3, 32, v3
	s_cmpk_lt_u32 s10, 0x100
	v_or3_b32 v0, v10, v0, v1
	v_bitop3_b32 v4, v2, s13, v3 bitop3:0xde
	v_bitop3_b32 v247, v2, s15, v3 bitop3:0xde
	s_cselect_b64 s[44:45], -1, 0
	s_and_b32 s13, s0, 0xffff
	v_add_u32_e32 v220, v0, v11
	v_lshlrev_b32_e32 v0, 11, v13
	s_mov_b32 s0, 0x38000
	v_mov_b32_e32 v2, 0x20000
	s_waitcnt vmcnt(6)
	v_pk_add_f32 v[36:37], v[36:37], 1.0 op_sel_hi:[1,0]
	v_pk_add_f32 v[38:39], v[38:39], 1.0 op_sel_hi:[1,0]
	v_pk_add_f32 v[40:41], v[40:41], 1.0 op_sel_hi:[1,0]
	v_pk_add_f32 v[42:43], v[42:43], 1.0 op_sel_hi:[1,0]
	v_pk_add_f32 v[44:45], v[44:45], 1.0 op_sel_hi:[1,0]
	v_pk_add_f32 v[46:47], v[46:47], 1.0 op_sel_hi:[1,0]
	v_pk_add_f32 v[48:49], v[48:49], 1.0 op_sel_hi:[1,0]
	v_pk_add_f32 v[50:51], v[50:51], 1.0 op_sel_hi:[1,0]
	v_pk_mul_f32 v[244:245], v[20:21], v[36:37]
	v_pk_mul_f32 v[242:243], v[22:23], v[38:39]
	v_pk_mul_f32 v[236:237], v[24:25], v[40:41]
	v_pk_mul_f32 v[234:235], v[26:27], v[42:43]
	v_pk_mul_f32 v[240:241], v[28:29], v[44:45]
	v_pk_mul_f32 v[238:239], v[30:31], v[46:47]
	v_pk_mul_f32 v[230:231], v[32:33], v[48:49]
	v_pk_mul_f32 v[228:229], v[34:35], v[50:51]
	v_bitop3_b32 v0, v0, s0, v2 bitop3:0xc8
	v_or3_b32 v0, v10, v0, v1
	s_add_i32 s70, 0, 0x10000
	s_add_i32 s71, 0, 0x14000
	s_ashr_i32 s67, s26, 31
	s_mov_b32 s68, s26
	s_ashr_i32 s69, s2, 31
	s_and_b32 s17, s1, 0xffff
	s_mov_b32 s19, 0x20000
	s_brev_b32 s18, -2
	s_and_b32 s21, s11, 0xffff
	v_mov_b32_e32 v221, v219
	v_add_u32_e32 v222, v0, v11
	v_mov_b32_e32 v223, v219
	v_mov_b64_e32 v[224:225], 0x100
	v_mov_b64_e32 v[226:227], 0xff
	v_add_u32_e32 v249, s70, v247
	v_add_u32_e32 v250, s71, v247
	v_add_u32_e32 v251, 0, v4
	v_mbcnt_hi_u32_b32 v252, -1, v209
	s_movk_i32 s72, 0x7ef
	s_movk_i32 s73, 0x7df
	s_movk_i32 s74, 0x7ff
	s_barrier
	s_branch .LBB0_451

;     __device__ __forceinline__ void operator()(const f32x4 (&acc)[2][2][4][2], const pg8::Unit& u, int wr, int wc, int fr, int fq) const {
;         const int b = u.pm >> 3, colb = u.pn * 256 + wc * 32 + 8 * fq; const int row0 = u.pm * 256 + wr * 64 + fr;
;         const float* mb = mod + b * NMOD;
;         f32x4 g1v[2][2], gm[2][2];
; #pragma unroll
;         for (int bj = 0; bj < 2; ++bj)
; #pragma unroll
;             for (int n = 0; n < 2; ++n) { const int col = colb + 128 * bj + 4 * n; g1v[bj][n] = *(const f32x4*)(mb + 2048 + col);
;                 gm[bj][n] = *(const f32x4*)(n2g + col) * (*(const f32x4*)(mb + 4096 + col) + 1.f); }
; #pragma unroll
;         for (int ai = 0; ai < 2; ++ai) {
;             f32x4 xv[4][2][2];
; #pragma unroll
;             for (int m = 0; m < 4; ++m)
; #pragma unroll
;                 for (int bj = 0; bj < 2; ++bj)
; #pragma unroll
;                     for (int n = 0; n < 2; ++n) xv[m][bj][n] = __builtin_nontemporal_load((const f32x4*)(x + ((unsigned)(row0 + ai * 128 + m * 16) * D_ + colb + 128 * bj + 4 * n)));
.LBB0_461:
	s_cmpk_lg_i32 s26, 0x100
	s_cbranch_scc1 .Lp4e_orig
	s_lshr_b32 s0, s22, 3
	s_lshl_b32 s49, s22, 8
	s_mul_i32 s22, s0, 0x1800
	s_ashr_i32 s23, s22, 31
	s_add_i32 s49, s49, s64
	s_lshl_b64 s[22:23], s[22:23], 2
	s_add_u32 s0, s36, s22
	s_addc_u32 s1, s37, s23
	s_add_u32 s22, s0, 0x2000
	v_lshl_or_b32 v232, s14, 8, v248
	s_addc_u32 s23, s1, 0
	s_add_u32 s54, s0, 0x4000
	v_ashrrev_i32_e32 v233, 31, v232
	s_addc_u32 s55, s1, 0
	v_or_b32_e32 v233, s49, v246
	v_lshl_add_u32 v218, v233, 10, v232
	s_lshl_b32 s0, s14, 2
	s_mov_b32 s14, s18
	s_mov_b32 s15, s19
	s_or_b32 s47, s0, s63
	v_lshlrev_b32_e32 v144, 2, v232
	global_load_dwordx4 v[64:67], v144, s[22:23] offset:16
	global_load_dwordx4 v[80:83], v144, s[22:23]
	global_load_dwordx4 v[68:71], v144, s[22:23] offset:512
	global_load_dwordx4 v[76:79], v144, s[22:23] offset:528
	v_lshl_add_u64 v[144:145], v[218:219], 2, s[30:31]
	s_nop 0
	global_load_dwordx4 v[200:203], v[144:145], off offset:16 nt
	global_load_dwordx4 v[204:207], v[144:145], off nt
	global_load_dwordx4 v[192:195], v[144:145], off offset:528 nt
	global_load_dwordx4 v[196:199], v[144:145], off offset:512 nt
	v_add_u32_e32 v144, 0x4000, v218
	v_mov_b32_e32 v145, v219
	v_lshl_add_u64 v[144:145], v[144:145], 2, s[30:31]
	global_load_dwordx4 v[184:187], v[144:145], off offset:16 nt
	global_load_dwordx4 v[188:191], v[144:145], off nt
	v_add_u32_e32 v144, 0x4080, v218
	v_mov_b32_e32 v145, v219
	v_lshl_add_u64 v[144:145], v[144:145], 2, s[30:31]
	global_load_dwordx4 v[176:179], v[144:145], off offset:16 nt
	global_load_dwordx4 v[180:183], v[144:145], off nt
	v_add_u32_e32 v144, 0x8000, v218
	v_mov_b32_e32 v145, v219
	v_lshl_add_u64 v[144:145], v[144:145], 2, s[30:31]
	global_load_dwordx4 v[168:171], v[144:145], off offset:16 nt
	global_load_dwordx4 v[172:175], v[144:145], off nt
	v_add_u32_e32 v144, 0x8080, v218
	v_mov_b32_e32 v145, v219
	v_lshl_add_u64 v[144:145], v[144:145], 2, s[30:31]
	global_load_dwordx4 v[160:163], v[144:145], off offset:16 nt
	global_load_dwordx4 v[164:167], v[144:145], off nt
	v_add_u32_e32 v144, 0xc000, v218
	v_mov_b32_e32 v145, v219
	v_lshl_add_u64 v[148:149], v[144:145], 2, s[30:31]
	global_load_dwordx4 v[144:147], v[148:149], off offset:16 nt
	global_load_dwordx4 v[152:155], v[148:149], off nt
	v_add_u32_e32 v148, 0xc080, v218
	v_mov_b32_e32 v149, v219
	v_lshl_add_u64 v[156:157], v[148:149], 2, s[30:31]
	global_load_dwordx4 v[148:151], v[156:157], off offset:16 nt
	s_nop 0
	global_load_dwordx4 v[156:159], v[156:157], off nt
	s_branch .Lp4e_join

; __device__ __forceinline__ unsigned pk2(float lo, float hi) { return pg8::cvt_pk_bf16(lo, hi); }
;     __device__ __forceinline__ void operator()(const f32x4 (&acc)[2][2][4][2], const pg8::Unit& u, int wr, int wc, int fr, int fq) const {
;     ...
;             for (int m = 0; m < 4; ++m) { const unsigned row = (unsigned)(row0 + ai * 128 + m * 16); float ss = 0.f;
; #pragma unroll
;                 for (int bj = 0; bj < 2; ++bj) { f32x4 x1[2]; u32x4 xb;
; #pragma unroll
;                     for (int n = 0; n < 2; ++n) {
;                         x1[n] = xv[m][bj][n] + g1v[bj][n] * acc[ai][bj][m][n];
;                         ss += (x1[n].x * x1[n].x + x1[n].y * x1[n].y) + (x1[n].z * x1[n].z + x1[n].w * x1[n].w); if (n == 0) { xb.x = pk2(x1[0].x, x1[0].y); xb.y = pk2(x1[0].z, x1[0].w); } else { xb.z = pk2(x1[1].x, x1[1].y); xb.w = pk2(x1[1].z, x1[1].w); } x1[n] = x1[n] * gm[bj][n]; }
;                     u32x4 w; w.x = pk2(x1[0].x, x1[0].y); w.y = pk2(x1[0].z, x1[0].w); w.z = pk2(x1[1].x, x1[1].y); w.w = pk2(x1[1].z, x1[1].w);
;                     st16wt(A2, (row * D_ + colb + 128 * bj) * 2u, w);
;                     st16wt(x1b, (row * D_ + colb + 128 * bj) * 2u, xb);
;                     { const unsigned t = row & (S_ - 1); if (t >= 2016u) st16wt(A2tail, (((row >> 11) * 32 + (t - 2016u)) * D_ + colb + 128 * bj) * 2u, w); } }
;                 ss += __shfl_xor(ss, 16); ss += __shfl_xor(ss, 32);
;                 if (fq == 0) rowss[row * 16 + u.pn * 4 + wc] = ss; }
.Lp4e_join:
	s_waitcnt vmcnt(15)
	v_pk_fma_f32 v[138:139], v[138:139], v[66:67], v[202:203]
	s_waitcnt vmcnt(14)
	v_pk_fma_f32 v[142:143], v[142:143], v[82:83], v[206:207]
	v_pk_fma_f32 v[204:205], v[140:141], v[80:81], v[204:205]
	v_mul_f32_e32 v141, v143, v143
	v_mul_f32_e32 v140, v205, v205
	v_fmac_f32_e32 v140, v204, v204
	v_fmac_f32_e32 v141, v142, v142
	v_pk_fma_f32 v[136:137], v[136:137], v[64:65], v[200:201]
	v_add_f32_e32 v253, v140, v141
	v_cvt_pk_bf16_f32 v140, v204, v205
	v_cvt_pk_bf16_f32 v141, v142, v143
	v_pk_mul_f32 v[206:207], v[242:243], v[142:143]
	v_mul_f32_e32 v142, v137, v137
	v_mul_f32_e32 v143, v139, v139
	v_fmac_f32_e32 v142, v136, v136
	v_fmac_f32_e32 v143, v138, v138
	v_add_f32_e32 v142, v142, v143
	v_add_f32_e32 v202, v253, v142
	v_cvt_pk_bf16_f32 v142, v136, v137
	v_cvt_pk_bf16_f32 v143, v138, v139
	v_pk_mul_f32 v[200:201], v[234:235], v[138:139]
	v_pk_mul_f32 v[138:139], v[236:237], v[136:137]
	v_pk_mul_f32 v[204:205], v[244:245], v[204:205]
	s_waitcnt vmcnt(12)
	v_pk_fma_f32 v[134:135], v[134:135], v[70:71], v[198:199]
	v_cvt_pk_bf16_f32 v136, v204, v205
	v_cvt_pk_bf16_f32 v137, v206, v207
	v_cvt_pk_bf16_f32 v138, v138, v139
	v_cvt_pk_bf16_f32 v139, v200, v201
	v_lshlrev_b32_e32 v200, 1, v218
	buffer_store_dwordx4 v[136:139], v200, s[16:19], 0 offen sc1
	v_pk_fma_f32 v[130:131], v[130:131], v[78:79], v[194:195]
	v_pk_fma_f32 v[128:129], v[128:129], v[76:77], v[192:193]
	v_pk_fma_f32 v[136:137], v[132:133], v[68:69], v[196:197]
	v_mul_f32_e32 v133, v135, v135
	v_mul_f32_e32 v132, v137, v137
	v_fmac_f32_e32 v132, v136, v136
	v_fmac_f32_e32 v133, v134, v134
	v_add_f32_e32 v132, v132, v133
	buffer_store_dwordx4 v[140:143], v200, s[12:15], 0 offen sc1
	v_pk_mul_f32 v[138:139], v[238:239], v[134:135]
	s_nop 0
	v_add_f32_e32 v140, v202, v132
	v_cvt_pk_bf16_f32 v132, v136, v137
	v_cvt_pk_bf16_f32 v133, v134, v135
	v_mul_f32_e32 v134, v129, v129
	v_mul_f32_e32 v135, v131, v131
	v_fmac_f32_e32 v134, v128, v128
	v_fmac_f32_e32 v135, v130, v130
	v_add_f32_e32 v134, v134, v135
	v_add_f32_e32 v142, v140, v134
	v_cvt_pk_bf16_f32 v134, v128, v129
	v_cvt_pk_bf16_f32 v135, v130, v131
	v_pk_mul_f32 v[140:141], v[228:229], v[130:131]
	v_pk_mul_f32 v[130:131], v[230:231], v[128:129]
	v_pk_mul_f32 v[136:137], v[240:241], v[136:137]
	s_nop 0
	v_cvt_pk_bf16_f32 v128, v136, v137
	v_cvt_pk_bf16_f32 v129, v138, v139
	v_cvt_pk_bf16_f32 v130, v130, v131
	v_cvt_pk_bf16_f32 v131, v140, v141
	buffer_store_dwordx4 v[128:131], v200, s[16:19], 0 offen offset:256 sc1
	buffer_store_dwordx4 v[132:135], v200, s[12:15], 0 offen offset:256 sc1
	s_nop 0
	v_and_b32_e32 v129, 64, v252
	v_xor_b32_e32 v128, 16, v252
	v_add_u32_e32 v129, 64, v129
	v_cmp_lt_i32_e32 vcc, v128, v129
	v_xor_b32_e32 v131, 32, v252
	s_nop 0
	v_cndmask_b32_e32 v128, v252, v128, vcc
	v_lshlrev_b32_e32 v128, 2, v128
	ds_bpermute_b32 v130, v128, v142
	v_cmp_lt_i32_e32 vcc, v131, v129
	s_waitcnt lgkmcnt(0)
	v_add_f32_e32 v130, v142, v130
	v_cndmask_b32_e32 v129, v252, v131, vcc
	v_lshlrev_b32_e32 v129, 2, v129
	ds_bpermute_b32 v131, v129, v130
	s_and_saveexec_b64 s[22:23], s[8:9]
	s_cbranch_execz .LBB0_463
	v_lshl_add_u32 v132, v233, 4, s47
	v_mov_b32_e32 v133, v219
	v_lshl_add_u64 v[132:133], v[132:133], 2, s[40:41]
	s_waitcnt lgkmcnt(0)
	v_add_f32_e32 v130, v130, v131
	global_store_dword v[132:133], v130, off sc1
